# GEMM residual epilogue software-pipelined across row groups; gv loads batched
# speedup vs baseline: 1.0590x; 1.0014x over previous
;     __device__ __forceinline__ void operator()(const f32x4 (&acc)[2][2][4][2], const Unit& u, int wr, int wc, int fr, int fq) const {
;         const int row0 = u.pm * BM + wr * 64 + fr, col0 = u.pn * BM + wc * 32 + 4 * fq;
;         const float* Rb = u.pm < 64 ? R0 : R1;
;         const int bi = u.pm < 64 ? (u.pm >> 3) : 8;
;         const float* mg = modg + (size_t)bi * 9216 + col0;
;         f32x4 gv[2][2];
; #pragma unroll
;         for (int bj = 0; bj < 2; ++bj)
; #pragma unroll
;             for (int n = 0; n < 2; ++n) gv[bj][n] = *(const f32x4*)(mg + bj * HALF + n * 16) * gs;
; #pragma unroll
;         for (int ai = 0; ai < 2; ++ai)
; #pragma unroll
;             for (int m = 0; m < 4; ++m) { float* rowp = X + (size_t)(row0 + ai * HALF + m * 16) * DM + col0;
; #pragma unroll
;                 for (int bj = 0; bj < 2; ++bj)
; #pragma unroll
;                     for (int n = 0; n < 2; ++n) { f32x4* q = (f32x4*)(rowp + bj * HALF + n * 16); const f32x4* rq = (const f32x4*)(Rb + (q - (f32x4*)X) * 4); *q = *rq + gv[bj][n] * acc[ai][bj][m][n]; } }
;     }
.LBB0_219:
	s_and_b64 s[42:43], s[56:57], exec
	s_cselect_b32 s57, s75, s77
	s_cselect_b32 s56, s76, s78
	v_lshl_or_b32 v140, s89, 8, v164
	s_lshl_b64 s[42:43], s[58:59], 2
	s_add_u32 s42, s73, s42
	v_ashrrev_i32_e32 v141, 31, v140
	s_addc_u32 s43, s74, s43
	v_lshlrev_b64 v[156:157], 2, v[140:141]
	v_lshl_add_u64 v[158:159], s[42:43], 0, v[156:157]
	global_load_dwordx4 v[140:143], v[158:159], off
	global_load_dwordx4 v[166:169], v[158:159], off offset:576
	global_load_dwordx4 v[242:245], v[158:159], off offset:64
	global_load_dwordx4 v[246:249], v[158:159], off offset:512
	v_mov_b32_e32 v133, v132
	v_lshl_add_u32 v160, s13, 8, v162
	v_ashrrev_i32_e32 v161, 31, v160
	s_mov_b64 s[42:43], 0x80000
	s_and_b64 vcc, exec, s[6:7]
	s_mov_b32 s89, s12
	s_mov_b32 s13, s93
	s_mov_b64 s[58:59], s[10:11]
	s_waitcnt vmcnt(0)
	v_pk_mul_f32 v[152:153], v[142:143], v[132:133]
	v_pk_mul_f32 v[154:155], v[140:141], v[134:135]
	v_pk_mul_f32 v[148:149], v[132:133], v[244:245]
	v_pk_mul_f32 v[150:151], v[134:135], v[242:243]
	v_lshlrev_b64 v[158:159], 12, v[160:161]
	v_pk_mul_f32 v[144:145], v[132:133], v[248:249]
	v_pk_mul_f32 v[142:143], v[134:135], v[166:167]
	v_pk_mul_f32 v[146:147], v[134:135], v[246:247]
	v_pk_mul_f32 v[140:141], v[132:133], v[168:169]
	s_mov_b32 s16, 0x0
	s_mov_b32 s17, 0
	v_lshl_add_u64 v[174:175], v[158:159], 0, s[16:17]
	v_lshl_add_u64 v[176:177], s[84:85], 0, v[174:175]
	v_lshl_add_u64 v[174:175], s[56:57], 0, v[174:175]
	v_lshl_add_u64 v[184:185], v[174:175], 0, v[156:157]
	v_lshl_add_u64 v[186:187], v[176:177], 0, v[156:157]
	global_load_dwordx4 v[204:207], v[184:185], off
	global_load_dwordx4 v[208:211], v[184:185], off offset:64
	global_load_dwordx4 v[212:215], v[184:185], off offset:512
	global_load_dwordx4 v[216:219], v[184:185], off offset:576
	s_mov_b32 s16, 0x10000
	s_mov_b32 s17, 0
	v_lshl_add_u64 v[188:189], v[158:159], 0, s[16:17]
	v_lshl_add_u64 v[190:191], s[84:85], 0, v[188:189]
	v_lshl_add_u64 v[188:189], s[56:57], 0, v[188:189]
	v_lshl_add_u64 v[194:195], v[188:189], 0, v[156:157]
	v_lshl_add_u64 v[220:221], v[190:191], 0, v[156:157]
	global_load_dwordx4 v[226:229], v[194:195], off
	global_load_dwordx4 v[230:233], v[194:195], off offset:64
	global_load_dwordx4 v[234:237], v[194:195], off offset:512
	global_load_dwordx4 v[238:241], v[194:195], off offset:576
	s_waitcnt vmcnt(7)
	v_pk_fma_f32 v[128:129], v[128:129], v[152:153], v[206:207]
	v_pk_fma_f32 v[126:127], v[126:127], v[154:155], v[204:205]
	global_store_dwordx4 v[186:187], v[126:129], off
	s_waitcnt vmcnt(7)
	v_pk_fma_f32 v[124:125], v[124:125], v[148:149], v[210:211]
	v_pk_fma_f32 v[122:123], v[122:123], v[150:151], v[208:209]
	global_store_dwordx4 v[186:187], v[122:125], off offset:64
	s_waitcnt vmcnt(7)
	v_pk_fma_f32 v[120:121], v[120:121], v[144:145], v[214:215]
	v_pk_fma_f32 v[118:119], v[118:119], v[146:147], v[212:213]
	global_store_dwordx4 v[186:187], v[118:121], off offset:512
	s_waitcnt vmcnt(7)
	v_pk_fma_f32 v[116:117], v[116:117], v[140:141], v[218:219]
	v_pk_fma_f32 v[114:115], v[114:115], v[142:143], v[216:217]
	global_store_dwordx4 v[186:187], v[114:117], off offset:576
	s_mov_b32 s16, 0x20000
	s_mov_b32 s17, 0
	v_lshl_add_u64 v[174:175], v[158:159], 0, s[16:17]
	v_lshl_add_u64 v[176:177], s[84:85], 0, v[174:175]
	v_lshl_add_u64 v[174:175], s[56:57], 0, v[174:175]
	v_lshl_add_u64 v[184:185], v[174:175], 0, v[156:157]
	v_lshl_add_u64 v[186:187], v[176:177], 0, v[156:157]
	global_load_dwordx4 v[204:207], v[184:185], off
	global_load_dwordx4 v[208:211], v[184:185], off offset:64
	global_load_dwordx4 v[212:215], v[184:185], off offset:512
	global_load_dwordx4 v[216:219], v[184:185], off offset:576
	s_waitcnt vmcnt(11)
	v_pk_fma_f32 v[112:113], v[112:113], v[152:153], v[228:229]
	v_pk_fma_f32 v[110:111], v[110:111], v[154:155], v[226:227]
	global_store_dwordx4 v[220:221], v[110:113], off
	s_waitcnt vmcnt(11)
	v_pk_fma_f32 v[108:109], v[108:109], v[148:149], v[232:233]
	v_pk_fma_f32 v[106:107], v[106:107], v[150:151], v[230:231]
	global_store_dwordx4 v[220:221], v[106:109], off offset:64
	s_waitcnt vmcnt(11)
	v_pk_fma_f32 v[104:105], v[104:105], v[144:145], v[236:237]
	v_pk_fma_f32 v[102:103], v[102:103], v[146:147], v[234:235]
	global_store_dwordx4 v[220:221], v[102:105], off offset:512
	s_waitcnt vmcnt(11)
	v_pk_fma_f32 v[100:101], v[100:101], v[140:141], v[240:241]
	v_pk_fma_f32 v[98:99], v[98:99], v[142:143], v[238:239]
	global_store_dwordx4 v[220:221], v[98:101], off offset:576
	s_mov_b32 s16, 0x30000
	s_mov_b32 s17, 0
	v_lshl_add_u64 v[188:189], v[158:159], 0, s[16:17]
	v_lshl_add_u64 v[190:191], s[84:85], 0, v[188:189]
	v_lshl_add_u64 v[188:189], s[56:57], 0, v[188:189]
	v_lshl_add_u64 v[194:195], v[188:189], 0, v[156:157]
	v_lshl_add_u64 v[220:221], v[190:191], 0, v[156:157]
	global_load_dwordx4 v[226:229], v[194:195], off
	global_load_dwordx4 v[230:233], v[194:195], off offset:64
	global_load_dwordx4 v[234:237], v[194:195], off offset:512
	global_load_dwordx4 v[238:241], v[194:195], off offset:576
	s_waitcnt vmcnt(11)
	v_pk_fma_f32 v[96:97], v[96:97], v[152:153], v[206:207]
	v_pk_fma_f32 v[94:95], v[94:95], v[154:155], v[204:205]
	global_store_dwordx4 v[186:187], v[94:97], off
	s_waitcnt vmcnt(11)
	v_pk_fma_f32 v[92:93], v[92:93], v[148:149], v[210:211]
	v_pk_fma_f32 v[90:91], v[90:91], v[150:151], v[208:209]
	global_store_dwordx4 v[186:187], v[90:93], off offset:64
	s_waitcnt vmcnt(11)
	v_pk_fma_f32 v[88:89], v[88:89], v[144:145], v[214:215]
	v_pk_fma_f32 v[86:87], v[86:87], v[146:147], v[212:213]
	global_store_dwordx4 v[186:187], v[86:89], off offset:512
	s_waitcnt vmcnt(11)
;     __device__ __forceinline__ void operator()(const f32x4 (&acc)[2][2][4][2], const Unit& u, int wr, int wc, int fr, int fq) const {
;         const int row0 = u.pm * BM + wr * 64 + fr, col0 = u.pn * BM + wc * 32 + 4 * fq;
;         const float* Rb = u.pm < 64 ? R0 : R1;
;         const int bi = u.pm < 64 ? (u.pm >> 3) : 8;
;         const float* mg = modg + (size_t)bi * 9216 + col0;
;         f32x4 gv[2][2];
; #pragma unroll
;         for (int bj = 0; bj < 2; ++bj)
; #pragma unroll
;             for (int n = 0; n < 2; ++n) gv[bj][n] = *(const f32x4*)(mg + bj * HALF + n * 16) * gs;
; #pragma unroll
;         for (int ai = 0; ai < 2; ++ai)
; #pragma unroll
;             for (int m = 0; m < 4; ++m) { float* rowp = X + (size_t)(row0 + ai * HALF + m * 16) * DM + col0;
; #pragma unroll
;                 for (int bj = 0; bj < 2; ++bj)
; #pragma unroll
;                     for (int n = 0; n < 2; ++n) { f32x4* q = (f32x4*)(rowp + bj * HALF + n * 16); const f32x4* rq = (const f32x4*)(Rb + (q - (f32x4*)X) * 4); *q = *rq + gv[bj][n] * acc[ai][bj][m][n]; } }
;     }
	v_pk_fma_f32 v[84:85], v[84:85], v[140:141], v[218:219]
	v_pk_fma_f32 v[82:83], v[82:83], v[142:143], v[216:217]
	global_store_dwordx4 v[186:187], v[82:85], off offset:576
	s_mov_b32 s16, 0x80000
	s_mov_b32 s17, 0
	v_lshl_add_u64 v[174:175], v[158:159], 0, s[16:17]
	v_lshl_add_u64 v[176:177], s[84:85], 0, v[174:175]
	v_lshl_add_u64 v[174:175], s[56:57], 0, v[174:175]
	v_lshl_add_u64 v[184:185], v[174:175], 0, v[156:157]
	v_lshl_add_u64 v[186:187], v[176:177], 0, v[156:157]
	global_load_dwordx4 v[204:207], v[184:185], off
	global_load_dwordx4 v[208:211], v[184:185], off offset:64
	global_load_dwordx4 v[212:215], v[184:185], off offset:512
	global_load_dwordx4 v[216:219], v[184:185], off offset:576
	s_waitcnt vmcnt(11)
	v_pk_fma_f32 v[80:81], v[80:81], v[152:153], v[228:229]
	v_pk_fma_f32 v[78:79], v[78:79], v[154:155], v[226:227]
	global_store_dwordx4 v[220:221], v[78:81], off
	s_waitcnt vmcnt(11)
	v_pk_fma_f32 v[76:77], v[76:77], v[148:149], v[232:233]
	v_pk_fma_f32 v[74:75], v[74:75], v[150:151], v[230:231]
	global_store_dwordx4 v[220:221], v[74:77], off offset:64
	s_waitcnt vmcnt(11)
	v_pk_fma_f32 v[72:73], v[72:73], v[144:145], v[236:237]
	v_pk_fma_f32 v[70:71], v[70:71], v[146:147], v[234:235]
	global_store_dwordx4 v[220:221], v[70:73], off offset:512
	s_waitcnt vmcnt(11)
	v_pk_fma_f32 v[68:69], v[68:69], v[140:141], v[240:241]
	v_pk_fma_f32 v[66:67], v[66:67], v[142:143], v[238:239]
	global_store_dwordx4 v[220:221], v[66:69], off offset:576
	s_mov_b32 s16, 0x90000
	s_mov_b32 s17, 0
	v_lshl_add_u64 v[188:189], v[158:159], 0, s[16:17]
	v_lshl_add_u64 v[190:191], s[84:85], 0, v[188:189]
	v_lshl_add_u64 v[188:189], s[56:57], 0, v[188:189]
	v_lshl_add_u64 v[194:195], v[188:189], 0, v[156:157]
	v_lshl_add_u64 v[220:221], v[190:191], 0, v[156:157]
	global_load_dwordx4 v[226:229], v[194:195], off
	global_load_dwordx4 v[230:233], v[194:195], off offset:64
	global_load_dwordx4 v[234:237], v[194:195], off offset:512
	global_load_dwordx4 v[238:241], v[194:195], off offset:576
	s_waitcnt vmcnt(11)
	v_pk_fma_f32 v[64:65], v[64:65], v[152:153], v[206:207]
	v_pk_fma_f32 v[62:63], v[62:63], v[154:155], v[204:205]
	global_store_dwordx4 v[186:187], v[62:65], off
	s_waitcnt vmcnt(11)
	v_pk_fma_f32 v[60:61], v[60:61], v[148:149], v[210:211]
	v_pk_fma_f32 v[58:59], v[58:59], v[150:151], v[208:209]
	global_store_dwordx4 v[186:187], v[58:61], off offset:64
	s_waitcnt vmcnt(11)
	v_pk_fma_f32 v[56:57], v[56:57], v[144:145], v[214:215]
	v_pk_fma_f32 v[54:55], v[54:55], v[146:147], v[212:213]
	global_store_dwordx4 v[186:187], v[54:57], off offset:512
	s_waitcnt vmcnt(11)
	v_pk_fma_f32 v[52:53], v[52:53], v[140:141], v[218:219]
	v_pk_fma_f32 v[50:51], v[50:51], v[142:143], v[216:217]
	global_store_dwordx4 v[186:187], v[50:53], off offset:576
	s_mov_b32 s16, 0xa0000
	s_mov_b32 s17, 0
	v_lshl_add_u64 v[174:175], v[158:159], 0, s[16:17]
	v_lshl_add_u64 v[176:177], s[84:85], 0, v[174:175]
	v_lshl_add_u64 v[174:175], s[56:57], 0, v[174:175]
	v_lshl_add_u64 v[184:185], v[174:175], 0, v[156:157]
	v_lshl_add_u64 v[186:187], v[176:177], 0, v[156:157]
	global_load_dwordx4 v[204:207], v[184:185], off
	global_load_dwordx4 v[208:211], v[184:185], off offset:64
	global_load_dwordx4 v[212:215], v[184:185], off offset:512
	global_load_dwordx4 v[216:219], v[184:185], off offset:576
	s_waitcnt vmcnt(11)
	v_pk_fma_f32 v[48:49], v[48:49], v[152:153], v[228:229]
	v_pk_fma_f32 v[46:47], v[46:47], v[154:155], v[226:227]
	global_store_dwordx4 v[220:221], v[46:49], off
	s_waitcnt vmcnt(11)
	v_pk_fma_f32 v[44:45], v[44:45], v[148:149], v[232:233]
	v_pk_fma_f32 v[42:43], v[42:43], v[150:151], v[230:231]
	global_store_dwordx4 v[220:221], v[42:45], off offset:64
	s_waitcnt vmcnt(11)
	v_pk_fma_f32 v[40:41], v[40:41], v[144:145], v[236:237]
	v_pk_fma_f32 v[38:39], v[38:39], v[146:147], v[234:235]
	global_store_dwordx4 v[220:221], v[38:41], off offset:512
	s_waitcnt vmcnt(11)
	v_pk_fma_f32 v[36:37], v[36:37], v[140:141], v[240:241]
	v_pk_fma_f32 v[34:35], v[34:35], v[142:143], v[238:239]
	global_store_dwordx4 v[220:221], v[34:37], off offset:576
	s_mov_b32 s16, 0xb0000
	s_mov_b32 s17, 0
	v_lshl_add_u64 v[188:189], v[158:159], 0, s[16:17]
	v_lshl_add_u64 v[190:191], s[84:85], 0, v[188:189]
	v_lshl_add_u64 v[188:189], s[56:57], 0, v[188:189]
	v_lshl_add_u64 v[194:195], v[188:189], 0, v[156:157]
	v_lshl_add_u64 v[220:221], v[190:191], 0, v[156:157]
	global_load_dwordx4 v[226:229], v[194:195], off
	global_load_dwordx4 v[230:233], v[194:195], off offset:64
	global_load_dwordx4 v[234:237], v[194:195], off offset:512
	global_load_dwordx4 v[238:241], v[194:195], off offset:576
	s_waitcnt vmcnt(11)
	v_pk_fma_f32 v[32:33], v[32:33], v[152:153], v[206:207]
	v_pk_fma_f32 v[30:31], v[30:31], v[154:155], v[204:205]
	global_store_dwordx4 v[186:187], v[30:33], off
	s_waitcnt vmcnt(11)
	v_pk_fma_f32 v[28:29], v[28:29], v[148:149], v[210:211]
	v_pk_fma_f32 v[26:27], v[26:27], v[150:151], v[208:209]
	global_store_dwordx4 v[186:187], v[26:29], off offset:64
	s_waitcnt vmcnt(11)
	v_pk_fma_f32 v[24:25], v[24:25], v[144:145], v[214:215]
	v_pk_fma_f32 v[22:23], v[22:23], v[146:147], v[212:213]
	global_store_dwordx4 v[186:187], v[22:25], off offset:512
	s_waitcnt vmcnt(11)
	v_pk_fma_f32 v[20:21], v[20:21], v[140:141], v[218:219]
	v_pk_fma_f32 v[18:19], v[18:19], v[142:143], v[216:217]
	global_store_dwordx4 v[186:187], v[18:21], off offset:576
	s_waitcnt vmcnt(7)
	v_pk_fma_f32 v[16:17], v[16:17], v[152:153], v[228:229]
	v_pk_fma_f32 v[14:15], v[14:15], v[154:155], v[226:227]
	global_store_dwordx4 v[220:221], v[14:17], off
	s_waitcnt vmcnt(7)
	v_pk_fma_f32 v[12:13], v[12:13], v[148:149], v[232:233]
	v_pk_fma_f32 v[10:11], v[10:11], v[150:151], v[230:231]
	global_store_dwordx4 v[220:221], v[10:13], off offset:64
	s_waitcnt vmcnt(7)
	v_pk_fma_f32 v[8:9], v[8:9], v[144:145], v[236:237]
	v_pk_fma_f32 v[6:7], v[6:7], v[146:147], v[234:235]
	global_store_dwordx4 v[220:221], v[6:9], off offset:512
	s_waitcnt vmcnt(7)
	v_pk_fma_f32 v[4:5], v[4:5], v[140:141], v[240:241]
	v_pk_fma_f32 v[2:3], v[2:3], v[142:143], v[238:239]
	global_store_dwordx4 v[220:221], v[2:5], off offset:576
	s_mov_b64 s[42:43], 0xb0000
	s_mov_b64 s[56:57], s[0:1]
	s_cbranch_vccnz .LBB0_234
